# no deferral; pipelined conversion with full-line stores; rows_first row loads all in flight; exchange slot reads parallel; gMLP sum-of-squares loads parallel; parallel first-barrier counter loads
# baseline (speedup 1.0000x reference)
; DI unsigned cvt_pk_bf16(float lo, float hi) { unsigned r; asm volatile("v_cvt_pk_bf16_f32 %0, %1, %2" : "=v"(r) : "v"(lo), "v"(hi)); return r; }
; DI void rows_first(const Ctx& cx, const float* __restrict__ x, bf16_t* __restrict__ xb, float* __restrict__ rrow) {
;     ...
;   for (int row = BID * 8 + wid; row < NTOK; row += NBLK * 8) {
;     float ss = 0.f;
; #pragma unroll
;     for (int i = 0; i < 8; ++i) { const size_t o = (size_t)row * 2048 + (i * 64 + lane) * 4; const f32x4 v = *(const f32x4*)(x + o);
;       ss += v.x * v.x + v.y * v.y + v.z * v.z + v.w * v.w;
;       u32x2 w; w.x = cvt_pk_bf16(v.x, v.y); w.y = cvt_pk_bf16(v.z, v.w); *(u32x2*)(xb + o) = w; }
;     ss = wave_sum(ss);
;     if (lane == 0) rrow[row] = rsqrtf(ss * (1.0f / 2048.0f) + EPS);
;   }
.LBB0_101:
	v_add_co_u32_e32 v14, vcc, 0xfffff000, v2
	v_and_b32_e32 v35, 64, v237
	s_nop 0
	v_addc_co_u32_e32 v15, vcc, -1, v3, vcc
	s_waitcnt lgkmcnt(0)
	global_load_dwordx4 v[64:67], v[14:15], off offset:-3072
	global_load_dwordx4 v[68:71], v[14:15], off offset:-2048
	global_load_dwordx4 v[72:75], v[14:15], off offset:-1024
	global_load_dwordx4 v[76:79], v[2:3], off offset:-4096
	global_load_dwordx4 v[80:83], v[2:3], off offset:-3072
	global_load_dwordx4 v[84:87], v[2:3], off offset:-2048
	global_load_dwordx4 v[88:91], v[2:3], off offset:-1024
	global_load_dwordx4 v[36:39], v[2:3], off
	v_add_u32_e32 v35, 64, v35
	v_xor_b32_e32 v42, 32, v237
	v_cmp_lt_i32_e32 vcc, v42, v35
	s_nop 1
	v_cndmask_b32_e32 v42, v237, v42, vcc
	v_lshlrev_b32_e32 v42, 2, v42
	s_waitcnt vmcnt(7)
	v_mul_f32_e32 v6, v65, v65
	v_fmac_f32_e32 v6, v64, v64
	v_fmac_f32_e32 v6, v66, v66
	v_fmac_f32_e32 v6, v67, v67
	v_cvt_pk_bf16_f32 v96, v64, v65
	v_cvt_pk_bf16_f32 v97, v66, v67
	global_store_dwordx2 v[4:5], v[96:97], off offset:-2048
	s_waitcnt vmcnt(7)
	v_mul_f32_e32 v7, v69, v69
	v_fmac_f32_e32 v7, v68, v68
	v_fmac_f32_e32 v7, v70, v70
	v_fmac_f32_e32 v7, v71, v71
	v_add_f32_e32 v6, v6, v7
	v_cvt_pk_bf16_f32 v98, v68, v69
	v_cvt_pk_bf16_f32 v99, v70, v71
	global_store_dwordx2 v[4:5], v[98:99], off offset:-1536
	s_waitcnt vmcnt(7)
	v_mul_f32_e32 v7, v73, v73
	v_fmac_f32_e32 v7, v72, v72
	v_fmac_f32_e32 v7, v74, v74
	v_fmac_f32_e32 v7, v75, v75
	v_add_f32_e32 v6, v6, v7
	v_cvt_pk_bf16_f32 v100, v72, v73
	v_cvt_pk_bf16_f32 v101, v74, v75
	global_store_dwordx2 v[4:5], v[100:101], off offset:-1024
	s_waitcnt vmcnt(7)
	v_mul_f32_e32 v7, v77, v77
	v_fmac_f32_e32 v7, v76, v76
	v_fmac_f32_e32 v7, v78, v78
	v_fmac_f32_e32 v7, v79, v79
	v_add_f32_e32 v6, v6, v7
	v_cvt_pk_bf16_f32 v102, v76, v77
	v_cvt_pk_bf16_f32 v103, v78, v79
	global_store_dwordx2 v[4:5], v[102:103], off offset:-512
	s_waitcnt vmcnt(7)
	v_mul_f32_e32 v7, v81, v81
	v_fmac_f32_e32 v7, v80, v80
	v_fmac_f32_e32 v7, v82, v82
	v_fmac_f32_e32 v7, v83, v83
	v_add_f32_e32 v6, v6, v7
	v_cvt_pk_bf16_f32 v96, v80, v81
	v_cvt_pk_bf16_f32 v97, v82, v83
	global_store_dwordx2 v[4:5], v[96:97], off
	s_waitcnt vmcnt(7)
	v_mul_f32_e32 v7, v85, v85
	v_fmac_f32_e32 v7, v84, v84
	v_fmac_f32_e32 v7, v86, v86
	v_fmac_f32_e32 v7, v87, v87
	v_add_f32_e32 v6, v6, v7
	v_cvt_pk_bf16_f32 v98, v84, v85
	v_cvt_pk_bf16_f32 v99, v86, v87
	global_store_dwordx2 v[4:5], v[98:99], off offset:512
	s_waitcnt vmcnt(7)
	v_mul_f32_e32 v7, v89, v89
	v_fmac_f32_e32 v7, v88, v88
	v_fmac_f32_e32 v7, v90, v90
	v_fmac_f32_e32 v7, v91, v91
	v_add_f32_e32 v6, v6, v7
	v_cvt_pk_bf16_f32 v100, v88, v89
	v_cvt_pk_bf16_f32 v101, v90, v91
	global_store_dwordx2 v[4:5], v[100:101], off offset:1024
	s_waitcnt vmcnt(7)
	v_mul_f32_e32 v7, v37, v37
	v_fmac_f32_e32 v7, v36, v36
	v_fmac_f32_e32 v7, v38, v38
	v_fmac_f32_e32 v7, v39, v39
	v_add_f32_e32 v6, v6, v7
	v_xor_b32_e32 v8, 16, v237
	v_cmp_lt_i32_e32 vcc, v8, v35
	ds_bpermute_b32 v7, v42, v6
	v_cndmask_b32_e32 v8, v237, v8, vcc
	v_lshlrev_b32_e32 v8, 2, v8
	s_waitcnt lgkmcnt(0)
	v_add_f32_e32 v6, v6, v7
	ds_bpermute_b32 v7, v8, v6
	v_xor_b32_e32 v8, 8, v237
	v_cmp_lt_i32_e32 vcc, v8, v35
	s_waitcnt lgkmcnt(0)
	v_add_f32_e32 v6, v6, v7
	v_cndmask_b32_e32 v8, v237, v8, vcc
	v_lshlrev_b32_e32 v8, 2, v8
	ds_bpermute_b32 v7, v8, v6
	v_xor_b32_e32 v8, 4, v237
	v_cmp_lt_i32_e32 vcc, v8, v35
	s_waitcnt lgkmcnt(0)
	v_add_f32_e32 v6, v6, v7
	v_cndmask_b32_e32 v8, v237, v8, vcc
	v_lshlrev_b32_e32 v8, 2, v8
	ds_bpermute_b32 v7, v8, v6
	v_xor_b32_e32 v8, 2, v237
	v_cmp_lt_i32_e32 vcc, v8, v35
	s_waitcnt lgkmcnt(0)
	v_add_f32_e32 v6, v6, v7
	v_cndmask_b32_e32 v8, v237, v8, vcc
	v_lshlrev_b32_e32 v8, 2, v8
	ds_bpermute_b32 v7, v8, v6
	v_xor_b32_e32 v8, 1, v237
	v_cmp_lt_i32_e32 vcc, v8, v35
	s_waitcnt lgkmcnt(0)
	v_add_f32_e32 v6, v6, v7
	v_cndmask_b32_e32 v8, v237, v8, vcc
	v_lshlrev_b32_e32 v7, 2, v8
	ds_bpermute_b32 v7, v7, v6
	v_cvt_pk_bf16_f32 v8, v36, v37
	v_cvt_pk_bf16_f32 v9, v38, v39
	global_store_dwordx2 v[4:5], v[8:9], off offset:1536
	s_and_saveexec_b64 s[42:43], s[34:35]
	s_cbranch_execz .LBB0_100
	s_waitcnt lgkmcnt(0)
	v_add_f32_e32 v6, v6, v7
	v_fmamk_f32 v6, v6, 0x3a000000, v235
	v_mul_f32_e32 v7, 0x4b800000, v6
	v_cmp_gt_f32_e32 vcc, s95, v6
	s_nop 1
	v_cndmask_b32_e32 v6, v6, v7, vcc
	v_rsq_f32_e32 v6, v6
	s_nop 0
	v_mul_f32_e32 v7, 0x45800000, v6
	v_cndmask_b32_e32 v6, v6, v7, vcc
	global_store_dword v[0:1], v6, off
	s_branch .LBB0_100

; #define LAS __attribute__((address_space(3)))
; template <bool GV_INTERLEAVE = false>
; DI void convert_chunk(const Ctx& cx, const float* __restrict__ src, bf16_t* __restrict__ dst, int K, int N, int tile0, int ntile, LAS unsigned char* lds, const float* __restrict__ gk = nullptr) {
;     ...
;     for (int h2 = 0; h2 < 2; ++h2) {
;       const int rn = (tid >> 3) + 64 * h2, rc = tid & 7;
;       const int sw = ((rn >> 2) & 7) << 1;
;       u32x2 a0 = *(LAS u32x2*)(L + rn * 66 + ((8 * rc) ^ sw)), a1 = *(LAS u32x2*)(L + rn * 66 + ((8 * rc + 2) ^ sw));
;       u32x2 a2 = *(LAS u32x2*)(L + rn * 66 + ((8 * rc + 4) ^ sw)), a3 = *(LAS u32x2*)(L + rn * 66 + ((8 * rc + 6) ^ sw));
; DI void run_phase(const Params& p, int ph, LAS unsigned char* lds, int wid_s) {
;     ...
;     unsigned* qctr = (unsigned*)(ws + OFF_BAR);
;     volatile LAS unsigned* qs = (volatile LAS unsigned*)(lds + 131072 + 8);
;     for (;;) {
;       if (TID == 0) *qs = __hip_atomic_fetch_add(qctr, 1u, __ATOMIC_RELAXED, __HIP_MEMORY_SCOPE_AGENT);
.LBB0_153:
	v_lshlrev_b32_e32 v1, 2, v242
	v_and_b32_e32 v2, 7, v242
	v_lshrrev_b32_e32 v3, 4, v242
	v_ashrrev_i32_e32 v0, 5, v242
	v_and_b32_e32 v32, 0x7c, v1
	v_lshlrev_b32_e32 v1, 1, v242
	v_and_b32_e32 v4, 14, v3
	v_lshlrev_b32_e32 v5, 3, v2
	v_bitop3_b32 v3, v5, v3, 14 bitop3:0x78
	v_bitop3_b32 v6, v5, v4, 2 bitop3:0x36
	v_bitop3_b32 v7, v5, v4, 4 bitop3:0x36
	v_bitop3_b32 v4, v5, v4, 6 bitop3:0x36
	v_bitop3_b32 v5, v1, v0, 14 bitop3:0x6c
	v_lshlrev_b32_e32 v5, 2, v5
	s_waitcnt lgkmcnt(0)
	v_mul_u32_u24_e32 v8, 0x108, v32
	v_add3_u32 v43, 0, v5, v8
	v_add_u32_e32 v5, 16, v0
	v_bitop3_b32 v5, v5, v1, 14 bitop3:0x78
	v_lshlrev_b32_e32 v5, 2, v5
	v_lshlrev_b32_e32 v33, 1, v0
	v_add3_u32 v44, 0, v5, v8
	v_add_u32_e32 v5, 32, v0
	v_add_u32_e32 v0, 48, v0
	v_ashrrev_i32_e32 v35, 3, v242
	s_movk_i32 s10, 0x108
	v_bitop3_b32 v0, v0, v1, 14 bitop3:0x78
	v_lshlrev_b32_e32 v34, 4, v2
	v_mul_lo_u32 v2, v35, s10
	v_lshlrev_b32_e32 v0, 2, v0
	v_add_u32_e32 v2, 0, v2
	v_lshlrev_b32_e32 v3, 2, v3
	v_bitop3_b32 v5, v5, v1, 14 bitop3:0x78
	v_add3_u32 v46, 0, v0, v8
	v_lshlrev_b32_e32 v0, 2, v6
	v_lshlrev_b32_e32 v1, 2, v7
	v_lshlrev_b32_e32 v4, 2, v4
	s_add_u32 s0, s2, 0x2a500000
	v_add_u32_e32 v42, v2, v3
	v_lshlrev_b32_e32 v5, 2, v5
	v_add_u32_e32 v47, v2, v0
	v_add_u32_e32 v48, v2, v1
	v_add_u32_e32 v49, v2, v4
	v_add_u32_e32 v50, 64, v35
	v_add_u32_e32 v2, 0x4200, v2
	s_addc_u32 s1, s3, 0
	v_cmp_eq_u32_e64 s[34:35], 0, v242
	v_add3_u32 v45, 0, v5, v8
	v_add_u32_e32 v51, v2, v3
	v_add_u32_e32 v52, v2, v0
	v_add_u32_e32 v53, v2, v1
	v_add_u32_e32 v54, v2, v4
	v_and_b32_e32 v55, 0x7f, v35
	v_and_b32_e32 v56, 0x7f, v50
	s_branch .LBB0_157

; DI void run_phase(const Params& p, int ph, LAS unsigned char* lds, int wid_s) {
;     ...
;       if (TID == 0) *qs = __hip_atomic_fetch_add(qctr, 1u, __ATOMIC_RELAXED, __HIP_MEMORY_SCOPE_AGENT);
;       __syncthreads();
;       const int chunk = (int)*qs;
;       __syncthreads();
;       if (chunk >= NCHUNK) break;
.LBB0_161:
	s_or_b64 exec, exec, s[22:23]
	v_mov_b32_e32 v0, s58
	s_waitcnt lgkmcnt(0)
	s_barrier
	ds_read_b32 v0, v0
	s_movk_i32 s11, 0x85f
	s_mov_b64 s[22:23], -1
	s_waitcnt lgkmcnt(0)
	s_barrier
	v_cmp_lt_i32_e32 vcc, s11, v0
	v_readfirstlane_b32 s10, v0
	s_cbranch_vccnz .LBB0_156

; #define LAS __attribute__((address_space(3)))
; template <bool GV_INTERLEAVE = false>
; DI void convert_chunk(const Ctx& cx, const float* __restrict__ src, bf16_t* __restrict__ dst, int K, int N, int tile0, int ntile, LAS unsigned char* lds, const float* __restrict__ gk = nullptr) {
;     ...
;   { const int tn = tile0 % tilesN, tk = tile0 / tilesN;
; #pragma unroll
;     for (int j = 0; j < 4; ++j)
; #pragma unroll
;       for (int r = 0; r < 2; ++r) v[j][r] = __builtin_nontemporal_load((const f32x4*)(src + (size_t)(tk * 128 + 32 * j + 2 * kp + r) * N + tn * 128 + 4 * n4)); }
;   for (int c = 0; c < ntile; ++c) {
;     const int tile = tile0 + c;
;     const int tn = tile % tilesN, tk = tile / tilesN;
;     const int k0 = tk * 128, n0 = tn * 128;
;     if (gk) {
; #pragma unroll
;       for (int j = 0; j < 4; ++j)
; #pragma unroll
;         for (int r = 0; r < 2; ++r) { const float g = gk[k0 + 32 * j + 2 * kp + r]; v[j][r] *= g; } }
;     __syncthreads();
; #pragma unroll
;     for (int j = 0; j < 4; ++j)
; #pragma unroll
;       for (int i = 0; i < 4; ++i) L[(4 * n4 + i) * 66 + ((16 * j + kp) ^ ((n4 & 7) << 1))] = cvt_pk_bf16(v[j][0][i], v[j][1][i]);
;     if (c + 1 < ntile) { const int t2 = tile + 1, tn2 = t2 % tilesN, tk2 = t2 / tilesN;
; #pragma unroll
;       for (int j = 0; j < 4; ++j)
; #pragma unroll
;         for (int r = 0; r < 2; ++r) v[j][r] = __builtin_nontemporal_load((const f32x4*)(src + (size_t)(tk2 * 128 + 32 * j + 2 * kp + r) * N + tn2 * 128 + 4 * n4)); }
;     __syncthreads();
; #pragma unroll
;     for (int h2 = 0; h2 < 2; ++h2) {
;       const int rn = (tid >> 3) + 64 * h2, rc = tid & 7;
;       const int sw = ((rn >> 2) & 7) << 1;
;       u32x2 a0 = *(LAS u32x2*)(L + rn * 66 + ((8 * rc) ^ sw)), a1 = *(LAS u32x2*)(L + rn * 66 + ((8 * rc + 2) ^ sw));
;       u32x2 a2 = *(LAS u32x2*)(L + rn * 66 + ((8 * rc + 4) ^ sw)), a3 = *(LAS u32x2*)(L + rn * 66 + ((8 * rc + 6) ^ sw));
;       int drow = n0 + rn;
;       if (GV_INTERLEAVE) { const int half = N >> 1; const int isv = drow >= half ? 1 : 0; const int f = drow - isv * half; drow = (f >> 7) * 256 + isv * 128 + (f & 127); }
;       bf16_t* d = dst + (size_t)drow * K + k0 + 16 * rc;
;       *(u32x4*)d = (u32x4){a0.x, a0.y, a1.x, a1.y};
;       *(u32x4*)(d + 8) = (u32x4){a2.x, a2.y, a3.x, a3.y};
.Lcv_common:
	s_mov_b32 s42, s30
	s_mov_b32 s43, s31
	s_lshr_b32 s82, s36, 1
	s_lshr_b32 s11, s36, 7
	v_mul_lo_u32 v184, v33, s38
	v_mul_lo_u32 v185, v35, s11
	v_lshlrev_b32_e32 v186, 2, v33
	v_lshl_add_u32 v184, v32, 2, v184
	v_add_u32_e32 v185, v34, v185
	v_lshrrev_b32_e32 v187, 2, v34
	v_lshrrev_b32_e32 v204, 1, v35
	v_and_b32_e32 v204, 14, v204
	v_xor_b32_e32 v187, v187, v204
	v_xor_b32_e32 v204, 2, v187
	v_mul_u32_u24_e32 v205, 0x108, v35
	v_lshl_add_u32 v187, v187, 2, v205
	v_lshl_add_u32 v204, v204, 2, v205
	s_mul_i32 s11, s31, s37
	s_lshl_b32 s12, s30, 9
	s_add_u32 s11, s11, s12
	s_add_u32 s74, s68, s11
	s_addc_u32 s75, s69, 0
	s_lshl_b32 s12, s31, 9
	s_add_u32 s80, s70, s12
	s_addc_u32 s81, s71, 0
	s_lshl_b32 s12, s38, 5
	global_load_dwordx2 v[160:161], v186, s[80:81]
	global_load_dwordx2 v[162:163], v186, s[80:81] offset:128
	global_load_dwordx2 v[164:165], v186, s[80:81] offset:256
	global_load_dwordx2 v[166:167], v186, s[80:81] offset:384
	global_load_dwordx4 v[64:67], v184, s[74:75] nt
	s_add_u32 s24, s74, s38
	s_addc_u32 s25, s75, 0
	global_load_dwordx4 v[68:71], v184, s[24:25] nt
	s_add_u32 s74, s74, s12
	s_addc_u32 s75, s75, 0
	global_load_dwordx4 v[72:75], v184, s[74:75] nt
	s_add_u32 s24, s74, s38
	s_addc_u32 s25, s75, 0
	global_load_dwordx4 v[76:79], v184, s[24:25] nt
	s_add_u32 s74, s74, s12
	s_addc_u32 s75, s75, 0
	global_load_dwordx4 v[80:83], v184, s[74:75] nt
	s_add_u32 s24, s74, s38
	s_addc_u32 s25, s75, 0
	global_load_dwordx4 v[84:87], v184, s[24:25] nt
	s_add_u32 s74, s74, s12
	s_addc_u32 s75, s75, 0
	global_load_dwordx4 v[88:91], v184, s[74:75] nt
	s_add_u32 s24, s74, s38
	s_addc_u32 s25, s75, 0
	global_load_dwordx4 v[92:95], v184, s[24:25] nt
	s_add_i32 s31, s31, 1
	s_mul_i32 s11, s31, s37
	s_lshl_b32 s12, s30, 9
	s_add_u32 s11, s11, s12
	s_add_u32 s74, s68, s11
	s_addc_u32 s75, s69, 0
	s_lshl_b32 s12, s31, 9
	s_add_u32 s80, s70, s12
	s_addc_u32 s81, s71, 0
	s_lshl_b32 s12, s38, 5
	global_load_dwordx2 v[168:169], v186, s[80:81]
	global_load_dwordx2 v[170:171], v186, s[80:81] offset:128
	global_load_dwordx2 v[172:173], v186, s[80:81] offset:256
	global_load_dwordx2 v[174:175], v186, s[80:81] offset:384
	global_load_dwordx4 v[96:99], v184, s[74:75] nt
	s_add_u32 s24, s74, s38
	s_addc_u32 s25, s75, 0
	global_load_dwordx4 v[100:103], v184, s[24:25] nt
	s_add_u32 s74, s74, s12
	s_addc_u32 s75, s75, 0
	global_load_dwordx4 v[104:107], v184, s[74:75] nt
	s_add_u32 s24, s74, s38
	s_addc_u32 s25, s75, 0
	global_load_dwordx4 v[108:111], v184, s[24:25] nt
	s_add_u32 s74, s74, s12
	s_addc_u32 s75, s75, 0
	global_load_dwordx4 v[112:115], v184, s[74:75] nt
	s_add_u32 s24, s74, s38
	s_addc_u32 s25, s75, 0
	global_load_dwordx4 v[116:119], v184, s[24:25] nt
	s_add_u32 s74, s74, s12
	s_addc_u32 s75, s75, 0
	global_load_dwordx4 v[120:123], v184, s[74:75] nt
	s_add_u32 s24, s74, s38
	s_addc_u32 s25, s75, 0
	global_load_dwordx4 v[124:127], v184, s[24:25] nt
	s_add_i32 s31, s31, 1
	s_mul_i32 s11, s31, s37
	s_lshl_b32 s12, s30, 9
	s_add_u32 s11, s11, s12
	s_add_u32 s74, s68, s11
	s_addc_u32 s75, s69, 0
	s_lshl_b32 s12, s31, 9
	s_add_u32 s80, s70, s12
	s_addc_u32 s81, s71, 0
	s_lshl_b32 s12, s38, 5
	global_load_dwordx2 v[176:177], v186, s[80:81]
	global_load_dwordx2 v[178:179], v186, s[80:81] offset:128
	global_load_dwordx2 v[180:181], v186, s[80:81] offset:256
	global_load_dwordx2 v[182:183], v186, s[80:81] offset:384
	global_load_dwordx4 v[128:131], v184, s[74:75] nt
	s_add_u32 s24, s74, s38
	s_addc_u32 s25, s75, 0
	global_load_dwordx4 v[132:135], v184, s[24:25] nt
	s_add_u32 s74, s74, s12
	s_addc_u32 s75, s75, 0
	global_load_dwordx4 v[136:139], v184, s[74:75] nt
	s_add_u32 s24, s74, s38
	s_addc_u32 s25, s75, 0
	global_load_dwordx4 v[140:143], v184, s[24:25] nt
	s_add_u32 s74, s74, s12
	s_addc_u32 s75, s75, 0
	global_load_dwordx4 v[144:147], v184, s[74:75] nt
	s_add_u32 s24, s74, s38
	s_addc_u32 s25, s75, 0
	global_load_dwordx4 v[148:151], v184, s[24:25] nt
	s_add_u32 s74, s74, s12
	s_addc_u32 s75, s75, 0
	global_load_dwordx4 v[152:155], v184, s[74:75] nt
	s_add_u32 s24, s74, s38
	s_addc_u32 s25, s75, 0
	global_load_dwordx4 v[156:159], v184, s[24:25] nt
	s_add_i32 s31, s31, 1
	s_waitcnt vmcnt(24)
	s_bitcmp1_b32 s41, 0
	s_cbranch_scc0 .Lcv_nomul0
	v_mul_f32_e32 v64, v64, v160
	v_mul_f32_e32 v65, v65, v160
	v_mul_f32_e32 v66, v66, v160
	v_mul_f32_e32 v67, v67, v160
	v_mul_f32_e32 v68, v68, v161
	v_mul_f32_e32 v69, v69, v161
	v_mul_f32_e32 v70, v70, v161
	v_mul_f32_e32 v71, v71, v161
	v_mul_f32_e32 v72, v72, v162
	v_mul_f32_e32 v73, v73, v162
	v_mul_f32_e32 v74, v74, v162
	v_mul_f32_e32 v75, v75, v162
	v_mul_f32_e32 v76, v76, v163
	v_mul_f32_e32 v77, v77, v163
	v_mul_f32_e32 v78, v78, v163
	v_mul_f32_e32 v79, v79, v163
	v_mul_f32_e32 v80, v80, v164
	v_mul_f32_e32 v81, v81, v164
	v_mul_f32_e32 v82, v82, v164
	v_mul_f32_e32 v83, v83, v164
	v_mul_f32_e32 v84, v84, v165
	v_mul_f32_e32 v85, v85, v165
	v_mul_f32_e32 v86, v86, v165
	v_mul_f32_e32 v87, v87, v165
	v_mul_f32_e32 v88, v88, v166
	v_mul_f32_e32 v89, v89, v166
	v_mul_f32_e32 v90, v90, v166
	v_mul_f32_e32 v91, v91, v166
	v_mul_f32_e32 v92, v92, v167
	v_mul_f32_e32 v93, v93, v167
	v_mul_f32_e32 v94, v94, v167
	v_mul_f32_e32 v95, v95, v167
; #define LAS __attribute__((address_space(3)))
; DI unsigned cvt_pk_bf16(float lo, float hi) { unsigned r; asm volatile("v_cvt_pk_bf16_f32 %0, %1, %2" : "=v"(r) : "v"(lo), "v"(hi)); return r; }
; template <bool GV_INTERLEAVE = false>
; DI void convert_chunk(const Ctx& cx, const float* __restrict__ src, bf16_t* __restrict__ dst, int K, int N, int tile0, int ntile, LAS unsigned char* lds, const float* __restrict__ gk = nullptr) {
;     ...
;     __syncthreads();
; #pragma unroll
;     for (int j = 0; j < 4; ++j)
; #pragma unroll
;       for (int i = 0; i < 4; ++i) L[(4 * n4 + i) * 66 + ((16 * j + kp) ^ ((n4 & 7) << 1))] = cvt_pk_bf16(v[j][0][i], v[j][1][i]);
;     if (c + 1 < ntile) { const int t2 = tile + 1, tn2 = t2 % tilesN, tk2 = t2 / tilesN;
; #pragma unroll
;       for (int j = 0; j < 4; ++j)
; #pragma unroll
;         for (int r = 0; r < 2; ++r) v[j][r] = __builtin_nontemporal_load((const f32x4*)(src + (size_t)(tk2 * 128 + 32 * j + 2 * kp + r) * N + tn2 * 128 + 4 * n4)); }
;     __syncthreads();
; #pragma unroll
;     for (int h2 = 0; h2 < 2; ++h2) {
;       const int rn = (tid >> 3) + 64 * h2, rc = tid & 7;
;       const int sw = ((rn >> 2) & 7) << 1;
;       u32x2 a0 = *(LAS u32x2*)(L + rn * 66 + ((8 * rc) ^ sw)), a1 = *(LAS u32x2*)(L + rn * 66 + ((8 * rc + 2) ^ sw));
;       u32x2 a2 = *(LAS u32x2*)(L + rn * 66 + ((8 * rc + 4) ^ sw)), a3 = *(LAS u32x2*)(L + rn * 66 + ((8 * rc + 6) ^ sw));
;       int drow = n0 + rn;
;       if (GV_INTERLEAVE) { const int half = N >> 1; const int isv = drow >= half ? 1 : 0; const int f = drow - isv * half; drow = (f >> 7) * 256 + isv * 128 + (f & 127); }
;       bf16_t* d = dst + (size_t)drow * K + k0 + 16 * rc;
;       *(u32x4*)d = (u32x4){a0.x, a0.y, a1.x, a1.y};
;       *(u32x4*)(d + 8) = (u32x4){a2.x, a2.y, a3.x, a3.y};
;     }
.Lcv_nomul0:
	v_cvt_pk_bf16_f32 v64, v64, v68
	ds_write_b32 v43, v64
	v_cvt_pk_bf16_f32 v65, v65, v69
	ds_write_b32 v43, v65 offset:264
	v_cvt_pk_bf16_f32 v66, v66, v70
	ds_write_b32 v43, v66 offset:528
	v_cvt_pk_bf16_f32 v67, v67, v71
	ds_write_b32 v43, v67 offset:792
	v_cvt_pk_bf16_f32 v72, v72, v76
	ds_write_b32 v43, v72 offset:64
	v_cvt_pk_bf16_f32 v73, v73, v77
	ds_write_b32 v43, v73 offset:328
	v_cvt_pk_bf16_f32 v74, v74, v78
	ds_write_b32 v43, v74 offset:592
	v_cvt_pk_bf16_f32 v75, v75, v79
	ds_write_b32 v43, v75 offset:856
	v_cvt_pk_bf16_f32 v80, v80, v84
	ds_write_b32 v43, v80 offset:128
	v_cvt_pk_bf16_f32 v81, v81, v85
	ds_write_b32 v43, v81 offset:392
	v_cvt_pk_bf16_f32 v82, v82, v86
	ds_write_b32 v43, v82 offset:656
	v_cvt_pk_bf16_f32 v83, v83, v87
	ds_write_b32 v43, v83 offset:920
	v_cvt_pk_bf16_f32 v88, v88, v92
	ds_write_b32 v43, v88 offset:192
	v_cvt_pk_bf16_f32 v89, v89, v93
	ds_write_b32 v43, v89 offset:456
	v_cvt_pk_bf16_f32 v90, v90, v94
	ds_write_b32 v43, v90 offset:720
	v_cvt_pk_bf16_f32 v91, v91, v95
	ds_write_b32 v43, v91 offset:984
	s_mul_i32 s11, s31, s37
	s_lshl_b32 s12, s30, 9
	s_add_u32 s11, s11, s12
	s_add_u32 s74, s68, s11
	s_addc_u32 s75, s69, 0
	s_lshl_b32 s12, s31, 9
	s_add_u32 s80, s70, s12
	s_addc_u32 s81, s71, 0
	s_lshl_b32 s12, s38, 5
	global_load_dwordx2 v[160:161], v186, s[80:81]
	global_load_dwordx2 v[162:163], v186, s[80:81] offset:128
	global_load_dwordx2 v[164:165], v186, s[80:81] offset:256
	global_load_dwordx2 v[166:167], v186, s[80:81] offset:384
	global_load_dwordx4 v[64:67], v184, s[74:75] nt
	s_add_u32 s24, s74, s38
	s_addc_u32 s25, s75, 0
	global_load_dwordx4 v[68:71], v184, s[24:25] nt
	s_add_u32 s74, s74, s12
	s_addc_u32 s75, s75, 0
	global_load_dwordx4 v[72:75], v184, s[74:75] nt
	s_add_u32 s24, s74, s38
	s_addc_u32 s25, s75, 0
	global_load_dwordx4 v[76:79], v184, s[24:25] nt
	s_add_u32 s74, s74, s12
	s_addc_u32 s75, s75, 0
	global_load_dwordx4 v[80:83], v184, s[74:75] nt
	s_add_u32 s24, s74, s38
	s_addc_u32 s25, s75, 0
	global_load_dwordx4 v[84:87], v184, s[24:25] nt
	s_add_u32 s74, s74, s12
	s_addc_u32 s75, s75, 0
	global_load_dwordx4 v[88:91], v184, s[74:75] nt
	s_add_u32 s24, s74, s38
	s_addc_u32 s25, s75, 0
	global_load_dwordx4 v[92:95], v184, s[24:25] nt
	s_add_i32 s31, s31, 1
	s_waitcnt lgkmcnt(0)
	s_barrier
	ds_read_b64 v[188:189], v187
	ds_read_b64 v[190:191], v204
	ds_read_b64 v[192:193], v187 offset:128
	ds_read_b64 v[194:195], v204 offset:128
	ds_read_b64 v[196:197], v187 offset:16896
	ds_read_b64 v[198:199], v204 offset:16896
	ds_read_b64 v[200:201], v187 offset:17024
	ds_read_b64 v[202:203], v204 offset:17024
	s_mov_b32 s11, s42
	s_bitcmp1_b32 s41, 1
	s_cbranch_scc0 .Lcv_ni0
	s_cmpk_ge_i32 s42, 44
	s_cselect_b32 s12, 44, 0
	s_cselect_b32 s22, 1, 0
	s_sub_i32 s11, s42, s12
	s_lshl_b32 s11, s11, 1
	s_or_b32 s11, s11, s22
.Lcv_ni0:
	s_mul_i32 s11, s11, s36
	s_lshl_b32 s12, s43, 8
	s_add_u32 s11, s11, s12
	s_add_u32 s76, s72, s11
	s_addc_u32 s77, s73, 0
	s_add_u32 s78, s76, s82
	s_addc_u32 s79, s77, 0
	s_add_i32 s43, s43, 1
	s_waitcnt lgkmcnt(6)
	global_store_dwordx4 v185, v[188:191], s[76:77]
	s_waitcnt lgkmcnt(4)
	global_store_dwordx4 v185, v[192:195], s[76:77] offset:128
	s_waitcnt lgkmcnt(2)
	global_store_dwordx4 v185, v[196:199], s[78:79]
	s_waitcnt lgkmcnt(0)
	global_store_dwordx4 v185, v[200:203], s[78:79] offset:128
	s_waitcnt vmcnt(28)
	s_bitcmp1_b32 s41, 0
	s_cbranch_scc0 .Lcv_nomul1
	v_mul_f32_e32 v96, v96, v168
	v_mul_f32_e32 v97, v97, v168
	v_mul_f32_e32 v98, v98, v168
	v_mul_f32_e32 v99, v99, v168
	v_mul_f32_e32 v100, v100, v169
	v_mul_f32_e32 v101, v101, v169
	v_mul_f32_e32 v102, v102, v169
	v_mul_f32_e32 v103, v103, v169
	v_mul_f32_e32 v104, v104, v170
	v_mul_f32_e32 v105, v105, v170
	v_mul_f32_e32 v106, v106, v170
	v_mul_f32_e32 v107, v107, v170
	v_mul_f32_e32 v108, v108, v171
	v_mul_f32_e32 v109, v109, v171
	v_mul_f32_e32 v110, v110, v171
	v_mul_f32_e32 v111, v111, v171
	v_mul_f32_e32 v112, v112, v172
	v_mul_f32_e32 v113, v113, v172
	v_mul_f32_e32 v114, v114, v172
	v_mul_f32_e32 v115, v115, v172
	v_mul_f32_e32 v116, v116, v173
	v_mul_f32_e32 v117, v117, v173
	v_mul_f32_e32 v118, v118, v173
	v_mul_f32_e32 v119, v119, v173
	v_mul_f32_e32 v120, v120, v174
	v_mul_f32_e32 v121, v121, v174
	v_mul_f32_e32 v122, v122, v174
	v_mul_f32_e32 v123, v123, v174
	v_mul_f32_e32 v124, v124, v175
	v_mul_f32_e32 v125, v125, v175
	v_mul_f32_e32 v126, v126, v175
	v_mul_f32_e32 v127, v127, v175
.Lcv_nomul1:
	v_cvt_pk_bf16_f32 v96, v96, v100
	ds_write_b32 v43, v96 offset:33792
	v_cvt_pk_bf16_f32 v97, v97, v101
	ds_write_b32 v43, v97 offset:34056
	v_cvt_pk_bf16_f32 v98, v98, v102
	ds_write_b32 v43, v98 offset:34320
	v_cvt_pk_bf16_f32 v99, v99, v103
	ds_write_b32 v43, v99 offset:34584
	v_cvt_pk_bf16_f32 v104, v104, v108
	ds_write_b32 v43, v104 offset:33856
	v_cvt_pk_bf16_f32 v105, v105, v109
	ds_write_b32 v43, v105 offset:34120
	v_cvt_pk_bf16_f32 v106, v106, v110
	ds_write_b32 v43, v106 offset:34384
	v_cvt_pk_bf16_f32 v107, v107, v111
	ds_write_b32 v43, v107 offset:34648
	v_cvt_pk_bf16_f32 v112, v112, v116
	ds_write_b32 v43, v112 offset:33920
	v_cvt_pk_bf16_f32 v113, v113, v117
	ds_write_b32 v43, v113 offset:34184
	v_cvt_pk_bf16_f32 v114, v114, v118
	ds_write_b32 v43, v114 offset:34448
	v_cvt_pk_bf16_f32 v115, v115, v119
	ds_write_b32 v43, v115 offset:34712
	v_cvt_pk_bf16_f32 v120, v120, v124
	ds_write_b32 v43, v120 offset:33984
	v_cvt_pk_bf16_f32 v121, v121, v125
	ds_write_b32 v43, v121 offset:34248
	v_cvt_pk_bf16_f32 v122, v122, v126
	ds_write_b32 v43, v122 offset:34512
	v_cvt_pk_bf16_f32 v123, v123, v127
	ds_write_b32 v43, v123 offset:34776
	s_waitcnt lgkmcnt(0)
	s_barrier
	ds_read_b64 v[188:189], v187 offset:33792
	ds_read_b64 v[190:191], v204 offset:33792
	ds_read_b64 v[192:193], v187 offset:33920
	ds_read_b64 v[194:195], v204 offset:33920
	ds_read_b64 v[196:197], v187 offset:50688
	ds_read_b64 v[198:199], v204 offset:50688
	ds_read_b64 v[200:201], v187 offset:50816
	ds_read_b64 v[202:203], v204 offset:50816
	s_mov_b32 s11, s42
	s_bitcmp1_b32 s41, 1
	s_cbranch_scc0 .Lcv_ni1
	s_cmpk_ge_i32 s42, 44
	s_cselect_b32 s12, 44, 0
	s_cselect_b32 s22, 1, 0
	s_sub_i32 s11, s42, s12
	s_lshl_b32 s11, s11, 1
	s_or_b32 s11, s11, s22
; #define LAS __attribute__((address_space(3)))
; DI unsigned cvt_pk_bf16(float lo, float hi) { unsigned r; asm volatile("v_cvt_pk_bf16_f32 %0, %1, %2" : "=v"(r) : "v"(lo), "v"(hi)); return r; }
; template <bool GV_INTERLEAVE = false>
; DI void convert_chunk(const Ctx& cx, const float* __restrict__ src, bf16_t* __restrict__ dst, int K, int N, int tile0, int ntile, LAS unsigned char* lds, const float* __restrict__ gk = nullptr) {
;     ...
;     __syncthreads();
; #pragma unroll
;     for (int j = 0; j < 4; ++j)
; #pragma unroll
;       for (int i = 0; i < 4; ++i) L[(4 * n4 + i) * 66 + ((16 * j + kp) ^ ((n4 & 7) << 1))] = cvt_pk_bf16(v[j][0][i], v[j][1][i]);
;     if (c + 1 < ntile) { const int t2 = tile + 1, tn2 = t2 % tilesN, tk2 = t2 / tilesN;
; #pragma unroll
;       for (int j = 0; j < 4; ++j)
; #pragma unroll
;         for (int r = 0; r < 2; ++r) v[j][r] = __builtin_nontemporal_load((const f32x4*)(src + (size_t)(tk2 * 128 + 32 * j + 2 * kp + r) * N + tn2 * 128 + 4 * n4)); }
;     __syncthreads();
; #pragma unroll
;     for (int h2 = 0; h2 < 2; ++h2) {
;       const int rn = (tid >> 3) + 64 * h2, rc = tid & 7;
;       const int sw = ((rn >> 2) & 7) << 1;
;       u32x2 a0 = *(LAS u32x2*)(L + rn * 66 + ((8 * rc) ^ sw)), a1 = *(LAS u32x2*)(L + rn * 66 + ((8 * rc + 2) ^ sw));
;       u32x2 a2 = *(LAS u32x2*)(L + rn * 66 + ((8 * rc + 4) ^ sw)), a3 = *(LAS u32x2*)(L + rn * 66 + ((8 * rc + 6) ^ sw));
;       int drow = n0 + rn;
;       if (GV_INTERLEAVE) { const int half = N >> 1; const int isv = drow >= half ? 1 : 0; const int f = drow - isv * half; drow = (f >> 7) * 256 + isv * 128 + (f & 127); }
;       bf16_t* d = dst + (size_t)drow * K + k0 + 16 * rc;
;       *(u32x4*)d = (u32x4){a0.x, a0.y, a1.x, a1.y};
;       *(u32x4*)(d + 8) = (u32x4){a2.x, a2.y, a3.x, a3.y};
;     }
.Lcv_ni1:
	s_mul_i32 s11, s11, s36
	s_lshl_b32 s12, s43, 8
	s_add_u32 s11, s11, s12
	s_add_u32 s76, s72, s11
	s_addc_u32 s77, s73, 0
	s_add_u32 s78, s76, s82
	s_addc_u32 s79, s77, 0
	s_add_i32 s43, s43, 1
	s_waitcnt lgkmcnt(6)
	global_store_dwordx4 v185, v[188:191], s[76:77]
	s_waitcnt lgkmcnt(4)
	global_store_dwordx4 v185, v[192:195], s[76:77] offset:128
	s_waitcnt lgkmcnt(2)
	global_store_dwordx4 v185, v[196:199], s[78:79]
	s_waitcnt lgkmcnt(0)
	global_store_dwordx4 v185, v[200:203], s[78:79] offset:128
	s_waitcnt vmcnt(20)
	s_bitcmp1_b32 s41, 0
	s_cbranch_scc0 .Lcv_nomul2
	v_mul_f32_e32 v128, v128, v176
	v_mul_f32_e32 v129, v129, v176
	v_mul_f32_e32 v130, v130, v176
	v_mul_f32_e32 v131, v131, v176
	v_mul_f32_e32 v132, v132, v177
	v_mul_f32_e32 v133, v133, v177
	v_mul_f32_e32 v134, v134, v177
	v_mul_f32_e32 v135, v135, v177
	v_mul_f32_e32 v136, v136, v178
	v_mul_f32_e32 v137, v137, v178
	v_mul_f32_e32 v138, v138, v178
	v_mul_f32_e32 v139, v139, v178
	v_mul_f32_e32 v140, v140, v179
	v_mul_f32_e32 v141, v141, v179
	v_mul_f32_e32 v142, v142, v179
	v_mul_f32_e32 v143, v143, v179
	v_mul_f32_e32 v144, v144, v180
	v_mul_f32_e32 v145, v145, v180
	v_mul_f32_e32 v146, v146, v180
	v_mul_f32_e32 v147, v147, v180
	v_mul_f32_e32 v148, v148, v181
	v_mul_f32_e32 v149, v149, v181
	v_mul_f32_e32 v150, v150, v181
	v_mul_f32_e32 v151, v151, v181
	v_mul_f32_e32 v152, v152, v182
	v_mul_f32_e32 v153, v153, v182
	v_mul_f32_e32 v154, v154, v182
	v_mul_f32_e32 v155, v155, v182
	v_mul_f32_e32 v156, v156, v183
	v_mul_f32_e32 v157, v157, v183
	v_mul_f32_e32 v158, v158, v183
	v_mul_f32_e32 v159, v159, v183
.Lcv_nomul2:
	v_cvt_pk_bf16_f32 v128, v128, v132
	ds_write_b32 v43, v128
	v_cvt_pk_bf16_f32 v129, v129, v133
	ds_write_b32 v43, v129 offset:264
	v_cvt_pk_bf16_f32 v130, v130, v134
	ds_write_b32 v43, v130 offset:528
	v_cvt_pk_bf16_f32 v131, v131, v135
	ds_write_b32 v43, v131 offset:792
	v_cvt_pk_bf16_f32 v136, v136, v140
	ds_write_b32 v43, v136 offset:64
	v_cvt_pk_bf16_f32 v137, v137, v141
	ds_write_b32 v43, v137 offset:328
	v_cvt_pk_bf16_f32 v138, v138, v142
	ds_write_b32 v43, v138 offset:592
	v_cvt_pk_bf16_f32 v139, v139, v143
	ds_write_b32 v43, v139 offset:856
	v_cvt_pk_bf16_f32 v144, v144, v148
	ds_write_b32 v43, v144 offset:128
	v_cvt_pk_bf16_f32 v145, v145, v149
	ds_write_b32 v43, v145 offset:392
	v_cvt_pk_bf16_f32 v146, v146, v150
	ds_write_b32 v43, v146 offset:656
	v_cvt_pk_bf16_f32 v147, v147, v151
	ds_write_b32 v43, v147 offset:920
	v_cvt_pk_bf16_f32 v152, v152, v156
	ds_write_b32 v43, v152 offset:192
	v_cvt_pk_bf16_f32 v153, v153, v157
	ds_write_b32 v43, v153 offset:456
	v_cvt_pk_bf16_f32 v154, v154, v158
	ds_write_b32 v43, v154 offset:720
	v_cvt_pk_bf16_f32 v155, v155, v159
	ds_write_b32 v43, v155 offset:984
	s_waitcnt lgkmcnt(0)
	s_barrier
	ds_read_b64 v[188:189], v187
	ds_read_b64 v[190:191], v204
	ds_read_b64 v[192:193], v187 offset:128
	ds_read_b64 v[194:195], v204 offset:128
	ds_read_b64 v[196:197], v187 offset:16896
	ds_read_b64 v[198:199], v204 offset:16896
	ds_read_b64 v[200:201], v187 offset:17024
	ds_read_b64 v[202:203], v204 offset:17024
	s_mov_b32 s11, s42
	s_bitcmp1_b32 s41, 1
	s_cbranch_scc0 .Lcv_ni2
	s_cmpk_ge_i32 s42, 44
	s_cselect_b32 s12, 44, 0
	s_cselect_b32 s22, 1, 0
	s_sub_i32 s11, s42, s12
	s_lshl_b32 s11, s11, 1
	s_or_b32 s11, s11, s22
; #define LAS __attribute__((address_space(3)))
; DI unsigned cvt_pk_bf16(float lo, float hi) { unsigned r; asm volatile("v_cvt_pk_bf16_f32 %0, %1, %2" : "=v"(r) : "v"(lo), "v"(hi)); return r; }
; template <bool GV_INTERLEAVE = false>
; DI void convert_chunk(const Ctx& cx, const float* __restrict__ src, bf16_t* __restrict__ dst, int K, int N, int tile0, int ntile, LAS unsigned char* lds, const float* __restrict__ gk = nullptr) {
;     ...
;     __syncthreads();
; #pragma unroll
;     for (int j = 0; j < 4; ++j)
; #pragma unroll
;       for (int i = 0; i < 4; ++i) L[(4 * n4 + i) * 66 + ((16 * j + kp) ^ ((n4 & 7) << 1))] = cvt_pk_bf16(v[j][0][i], v[j][1][i]);
;     if (c + 1 < ntile) { const int t2 = tile + 1, tn2 = t2 % tilesN, tk2 = t2 / tilesN;
; #pragma unroll
;       for (int j = 0; j < 4; ++j)
; #pragma unroll
;         for (int r = 0; r < 2; ++r) v[j][r] = __builtin_nontemporal_load((const f32x4*)(src + (size_t)(tk2 * 128 + 32 * j + 2 * kp + r) * N + tn2 * 128 + 4 * n4)); }
;     __syncthreads();
; #pragma unroll
;     for (int h2 = 0; h2 < 2; ++h2) {
;       const int rn = (tid >> 3) + 64 * h2, rc = tid & 7;
;       const int sw = ((rn >> 2) & 7) << 1;
;       u32x2 a0 = *(LAS u32x2*)(L + rn * 66 + ((8 * rc) ^ sw)), a1 = *(LAS u32x2*)(L + rn * 66 + ((8 * rc + 2) ^ sw));
;       u32x2 a2 = *(LAS u32x2*)(L + rn * 66 + ((8 * rc + 4) ^ sw)), a3 = *(LAS u32x2*)(L + rn * 66 + ((8 * rc + 6) ^ sw));
;       int drow = n0 + rn;
;       if (GV_INTERLEAVE) { const int half = N >> 1; const int isv = drow >= half ? 1 : 0; const int f = drow - isv * half; drow = (f >> 7) * 256 + isv * 128 + (f & 127); }
;       bf16_t* d = dst + (size_t)drow * K + k0 + 16 * rc;
;       *(u32x4*)d = (u32x4){a0.x, a0.y, a1.x, a1.y};
;       *(u32x4*)(d + 8) = (u32x4){a2.x, a2.y, a3.x, a3.y};
;     }
.Lcv_ni2:
	s_mul_i32 s11, s11, s36
	s_lshl_b32 s12, s43, 8
	s_add_u32 s11, s11, s12
	s_add_u32 s76, s72, s11
	s_addc_u32 s77, s73, 0
	s_add_u32 s78, s76, s82
	s_addc_u32 s79, s77, 0
	s_add_i32 s43, s43, 1
	s_waitcnt lgkmcnt(6)
	global_store_dwordx4 v185, v[188:191], s[76:77]
	s_waitcnt lgkmcnt(4)
	global_store_dwordx4 v185, v[192:195], s[76:77] offset:128
	s_waitcnt lgkmcnt(2)
	global_store_dwordx4 v185, v[196:199], s[78:79]
	s_waitcnt lgkmcnt(0)
	global_store_dwordx4 v185, v[200:203], s[78:79] offset:128
	s_waitcnt vmcnt(12)
	s_bitcmp1_b32 s41, 0
	s_cbranch_scc0 .Lcv_nomul3
	v_mul_f32_e32 v64, v64, v160
	v_mul_f32_e32 v65, v65, v160
	v_mul_f32_e32 v66, v66, v160
	v_mul_f32_e32 v67, v67, v160
	v_mul_f32_e32 v68, v68, v161
	v_mul_f32_e32 v69, v69, v161
	v_mul_f32_e32 v70, v70, v161
	v_mul_f32_e32 v71, v71, v161
	v_mul_f32_e32 v72, v72, v162
	v_mul_f32_e32 v73, v73, v162
	v_mul_f32_e32 v74, v74, v162
	v_mul_f32_e32 v75, v75, v162
	v_mul_f32_e32 v76, v76, v163
	v_mul_f32_e32 v77, v77, v163
	v_mul_f32_e32 v78, v78, v163
	v_mul_f32_e32 v79, v79, v163
	v_mul_f32_e32 v80, v80, v164
	v_mul_f32_e32 v81, v81, v164
	v_mul_f32_e32 v82, v82, v164
	v_mul_f32_e32 v83, v83, v164
	v_mul_f32_e32 v84, v84, v165
	v_mul_f32_e32 v85, v85, v165
	v_mul_f32_e32 v86, v86, v165
	v_mul_f32_e32 v87, v87, v165
	v_mul_f32_e32 v88, v88, v166
	v_mul_f32_e32 v89, v89, v166
	v_mul_f32_e32 v90, v90, v166
	v_mul_f32_e32 v91, v91, v166
	v_mul_f32_e32 v92, v92, v167
	v_mul_f32_e32 v93, v93, v167
	v_mul_f32_e32 v94, v94, v167
	v_mul_f32_e32 v95, v95, v167
.Lcv_nomul3:
	v_cvt_pk_bf16_f32 v64, v64, v68
	ds_write_b32 v43, v64 offset:33792
	v_cvt_pk_bf16_f32 v65, v65, v69
	ds_write_b32 v43, v65 offset:34056
	v_cvt_pk_bf16_f32 v66, v66, v70
	ds_write_b32 v43, v66 offset:34320
	v_cvt_pk_bf16_f32 v67, v67, v71
	ds_write_b32 v43, v67 offset:34584
	v_cvt_pk_bf16_f32 v72, v72, v76
	ds_write_b32 v43, v72 offset:33856
	v_cvt_pk_bf16_f32 v73, v73, v77
	ds_write_b32 v43, v73 offset:34120
	v_cvt_pk_bf16_f32 v74, v74, v78
	ds_write_b32 v43, v74 offset:34384
	v_cvt_pk_bf16_f32 v75, v75, v79
	ds_write_b32 v43, v75 offset:34648
	v_cvt_pk_bf16_f32 v80, v80, v84
	ds_write_b32 v43, v80 offset:33920
	v_cvt_pk_bf16_f32 v81, v81, v85
	ds_write_b32 v43, v81 offset:34184
	v_cvt_pk_bf16_f32 v82, v82, v86
	ds_write_b32 v43, v82 offset:34448
	v_cvt_pk_bf16_f32 v83, v83, v87
	ds_write_b32 v43, v83 offset:34712
	v_cvt_pk_bf16_f32 v88, v88, v92
	ds_write_b32 v43, v88 offset:33984
	v_cvt_pk_bf16_f32 v89, v89, v93
	ds_write_b32 v43, v89 offset:34248
	v_cvt_pk_bf16_f32 v90, v90, v94
	ds_write_b32 v43, v90 offset:34512
	v_cvt_pk_bf16_f32 v91, v91, v95
	ds_write_b32 v43, v91 offset:34776
	s_waitcnt lgkmcnt(0)
	s_barrier
	ds_read_b64 v[188:189], v187 offset:33792
	ds_read_b64 v[190:191], v204 offset:33792
	ds_read_b64 v[192:193], v187 offset:33920
	ds_read_b64 v[194:195], v204 offset:33920
	ds_read_b64 v[196:197], v187 offset:50688
	ds_read_b64 v[198:199], v204 offset:50688
	ds_read_b64 v[200:201], v187 offset:50816
	ds_read_b64 v[202:203], v204 offset:50816
	s_mov_b32 s11, s42
	s_bitcmp1_b32 s41, 1
	s_cbranch_scc0 .Lcv_ni3
	s_cmpk_ge_i32 s42, 44
	s_cselect_b32 s12, 44, 0
	s_cselect_b32 s22, 1, 0
	s_sub_i32 s11, s42, s12
	s_lshl_b32 s11, s11, 1
	s_or_b32 s11, s11, s22
.Lcv_ni3:
	s_mul_i32 s11, s11, s36
	s_lshl_b32 s12, s43, 8
	s_add_u32 s11, s11, s12
	s_add_u32 s76, s72, s11
	s_addc_u32 s77, s73, 0
	s_add_u32 s78, s76, s82
	s_addc_u32 s79, s77, 0
	s_add_i32 s43, s43, 1
	s_waitcnt lgkmcnt(6)
	global_store_dwordx4 v185, v[188:191], s[76:77]
	s_waitcnt lgkmcnt(4)
	global_store_dwordx4 v185, v[192:195], s[76:77] offset:128
	s_waitcnt lgkmcnt(2)
	global_store_dwordx4 v185, v[196:199], s[78:79]
	s_waitcnt lgkmcnt(0)
	global_store_dwordx4 v185, v[200:203], s[78:79] offset:128
	s_branch .LBB0_157

; #define PG8_WAIT_V(n) asm volatile("s_waitcnt vmcnt(" #n ")" ::: "memory")
; #define PG8_BAR __builtin_amdgcn_s_barrier()
; template <class Epi, class Sched>
; DI void gemm_phase(LAS unsigned char* lds, const Sched& S, const Epi& E) {
;     ...
;   PG8_WAIT_V(0);
;   PG8_BAR;
;   if constexpr (Epi::AFTER_DRAIN) E.fused(acc, cur, wr, wc, fr, fq, lds, tid);
; DI void run_phase(const Params& p, int ph, LAS unsigned char* lds, int wid_s) {
;     ...
;   } else if (s == 5) {
;     pg8::SchedPlain S; S.cx = cx; S.A = (const char*)hbuf; S.Bt = (const char*)(wl + WL_WUP); S.nM = 32; S.nN = 44; S.K = 2048;
;     pg8::EpiUpConv E; E.act = act; E.cw = p.in[18] + (size_t)l * 3 * D_FF; E.cb = p.in[19] + (size_t)l * D_FF;
;     E.tailg = sideb; E.headg = sideb + (size_t)256 * D_FF; E.headv = sideb + (size_t)512 * D_FF; E.rrow = rrow;
;     pg8::gemm_phase(lds, S, E);
.LBB0_498:
	s_waitcnt vmcnt(0)
	v_readlane_b32 s88, v254, 47
	v_readlane_b32 s89, v254, 48
	s_barrier
.LBB0_499:
	s_mov_b64 s[90:91], 0
	s_branch .LBB0_767
